# speedup vs baseline: 1.0101x; 1.0068x over previous
; #define LAS __attribute__((address_space(3)))
; __device__ __forceinline__ void tile_body(bool DIAG, const LAS unsigned char* kb, const LAS unsigned char* vb, int krow, int jm, int hh, int rr, float d00, float m2, float sm2, float M0,
;                                           const bf16x8 (&qf)[4], f32x16 (&O)[4], float& ls) {
;     ...
;         for (int t4 = 0; t4 < 4; ++t4) { const int c = jm * 8 + 2 * t4 + hh, kr = 32 * sb + krow;
;             kf[sb][t4] = *(const LAS bf16x8*)(kb + kr * 256 + ((c ^ (kr & 15)) * 16)); }
;     f32x16 s0, s1;
;     if (!DIAG) { const float base0 = -M0 - sm2 * d00, base1 = base0 + sm2 * 32.0f;
; #pragma unroll
;         for (int r = 0; r < 16; ++r) { const float cr = (float)(16 * (r >> 3) + (r & 7)); s0[r] = fmaf(sm2, cr, base0); s1[r] = fmaf(sm2, cr, base1); }
;     } else {
; #pragma unroll
;         for (int r = 0; r < 16; ++r) { const float cr = (float)(16 * (r >> 3) + (r & 7)); s0[r] = fmaf(-m2, fabsf(d00 - cr), -M0); s1[r] = fmaf(-m2, fabsf(d00 - 32.0f - cr), -M0); }
;     }
; __device__ __forceinline__ void attn_phase(LAS unsigned char* lds, const bf16_t* Z, const bf16_t* VT, bf16_t* Y, const float* subln, float lam, float lam_init, float M0, unsigned* ctr, LAS int* s_unit, int wid_s_) {
;     ...
;             for (int half = 0; half < 2; ++half) { const int t = 2 * T + half;
;                 if (t >= wlo && t <= whi) {
;                     const LAS unsigned char* kb = lds + (2 * b + half) * BUF; const LAS unsigned char* vb = kb + KBYTES;
;                     const int k0 = t * 64;
;                     const float d00 = (float)(qw + rr - (k0 + 8 * hh));
;                     const bool left = (k0 + 63 <= qw), right = (k0 >= qw + 31);
;                     tile_body(!(left || right), kb, vb, krow, jm, hh, rr, d00, m2, right ? -m2 : m2, M0, qf, O, ls);
.LBB0_1303:
	s_cmp_lt_u32 s26, s51
	s_cbranch_scc1 .LBB0_1309
	s_cmp_gt_i32 s26, s84
	s_cbranch_scc1 .LBB0_1309
	ds_read_b128 v[114:117], v180
	ds_read_b128 v[130:133], v180 offset:8192
	ds_read_b128 v[118:121], v181
	ds_read_b128 v[134:137], v181 offset:8192
	ds_read_b128 v[122:125], v182
	ds_read_b128 v[138:141], v182 offset:8192
	ds_read_b128 v[126:129], v183
	ds_read_b128 v[142:145], v183 offset:8192
	s_add_i32 s2, s85, 63
	v_cvt_f32_i32_e32 v184, v193
	s_cmp_lt_i32 s85, s50
	s_cselect_b64 s[16:17], -1, 0
	s_cbranch_scc0 .Llin0
	s_cmp_le_i32 s2, s40
	s_cbranch_scc0 .Ldiag0
.Llin0:
	v_cndmask_b32_e64 v78, -v171, v171, s[16:17]
	v_fma_f32 v94, -v78, v184, -v201
	v_fmamk_f32 v218, v78, 0x42000000, v94
	v_fma_f32 v80, 0, v78, v94
	v_fma_f32 v64, 0, v78, v218
	v_add_f32_e32 v81, v78, v94
	v_add_f32_e32 v65, v78, v218
	v_fma_f32 v82, v78, s80, v94
	v_fma_f32 v83, v78, s81, v94
	v_fma_f32 v66, v78, s80, v218
	v_fma_f32 v67, v78, s81, v218
	v_fma_f32 v84, v78, s66, v94
	v_fma_f32 v85, v78, s67, v94
	v_fma_f32 v68, v78, s66, v218
	v_fma_f32 v69, v78, s67, v218
	v_fma_f32 v86, v78, s74, v94
	v_fma_f32 v87, v78, s75, v94
	v_fma_f32 v70, v78, s74, v218
	v_fma_f32 v71, v78, s75, v218
	v_fma_f32 v88, v78, s34, v94
	v_fma_f32 v89, v78, s35, v94
	v_fma_f32 v72, v78, s34, v218
	v_fma_f32 v73, v78, s35, v218
	v_fma_f32 v90, v78, s96, v94
	v_fma_f32 v91, v78, s97, v94
	v_fma_f32 v74, v78, s96, v218
	v_fma_f32 v75, v78, s97, v218
	v_fma_f32 v92, v78, s52, v94
	v_fma_f32 v93, v78, s53, v94
	v_fma_f32 v76, v78, s52, v218
	v_fma_f32 v77, v78, s53, v218
	v_fma_f32 v95, v78, s55, v94
	v_fma_f32 v94, v78, s54, v94
	v_fma_f32 v79, v78, s55, v218
	v_fma_f32 v78, v78, s54, v218
	s_branch .LBB0_1308
.Ldiag0:
	v_pk_add_f32 v[66:67], v[184:185], s[56:57] op_sel_hi:[0,1]
	v_pk_add_f32 v[82:83], v[184:185], s[38:39] op_sel_hi:[0,1]
	v_add_f32_e32 v65, -1.0, v184
	v_add_f32_e32 v64, 0xc2000000, v184
	v_pk_add_f32 v[70:71], v[184:185], s[58:59] op_sel_hi:[0,1]
	v_pk_add_f32 v[74:75], v[184:185], s[60:61] op_sel_hi:[0,1]
	v_pk_add_f32 v[80:81], v[184:185], s[64:65] op_sel_hi:[0,1]
	v_pk_add_f32 v[84:85], v[184:185], s[30:31] op_sel_hi:[0,1]
	v_and_b32_e32 v67, 0x7fffffff, v67
	v_and_b32_e32 v66, 0x7fffffff, v66
	v_and_b32_e32 v83, 0x7fffffff, v83
	v_and_b32_e32 v82, 0x7fffffff, v82
	v_mov_b32_e32 v153, v152
	v_mov_b32_e32 v173, v172
	v_add_f32_e32 v192, -1.0, v64
	v_pk_add_f32 v[68:69], v[64:65], s[56:57] op_sel_hi:[0,1]
	v_pk_add_f32 v[72:73], v[64:65], s[58:59] op_sel_hi:[0,1]
	v_pk_add_f32 v[76:77], v[64:65], s[60:61] op_sel_hi:[0,1]
	v_pk_add_f32 v[78:79], v[184:185], s[62:63] op_sel_hi:[0,1]
	v_pk_add_f32 v[218:219], v[64:65], s[62:63] op_sel_hi:[0,1]
	v_pk_add_f32 v[220:221], v[64:65], s[64:65] op_sel_hi:[0,1]
	v_pk_add_f32 v[222:223], v[64:65], s[38:39] op_sel_hi:[0,1]
	v_and_b32_e32 v71, 0x7fffffff, v71
	v_and_b32_e32 v70, 0x7fffffff, v70
	v_and_b32_e32 v75, 0x7fffffff, v75
	v_and_b32_e32 v74, 0x7fffffff, v74
	v_and_b32_e32 v81, 0x7fffffff, v81
	v_and_b32_e32 v80, 0x7fffffff, v80
	v_and_b32_e32 v85, 0x7fffffff, v85
	v_and_b32_e32 v84, 0x7fffffff, v84
	v_and_b32_e32 v224, 0x7fffffff, v184
	v_and_b32_e32 v225, 0x7fffffff, v65
	v_pk_fma_f32 v[92:93], v[172:173], v[82:83], v[152:153]
	v_pk_fma_f32 v[82:83], v[172:173], v[66:67], v[152:153]
	v_pk_add_f32 v[66:67], v[64:65], s[30:31] op_sel_hi:[0,1]
	v_and_b32_e32 v79, 0x7fffffff, v79
	v_and_b32_e32 v78, 0x7fffffff, v78
	v_pk_fma_f32 v[94:95], v[172:173], v[84:85], v[152:153]
	v_pk_fma_f32 v[90:91], v[172:173], v[80:81], v[152:153]
	v_pk_fma_f32 v[86:87], v[172:173], v[74:75], v[152:153]
	v_pk_fma_f32 v[84:85], v[172:173], v[70:71], v[152:153]
	v_pk_fma_f32 v[80:81], v[174:175], v[224:225], v[154:155]
	v_and_b32_e32 v225, 0x7fffffff, v69
	v_and_b32_e32 v224, 0x7fffffff, v68
	v_and_b32_e32 v69, 0x7fffffff, v73
	v_and_b32_e32 v68, 0x7fffffff, v72
	v_and_b32_e32 v71, 0x7fffffff, v77
	v_and_b32_e32 v70, 0x7fffffff, v76
	v_and_b32_e32 v73, 0x7fffffff, v219
	v_and_b32_e32 v72, 0x7fffffff, v218
	v_and_b32_e32 v75, 0x7fffffff, v221
	v_and_b32_e32 v74, 0x7fffffff, v220
	v_and_b32_e32 v77, 0x7fffffff, v223
	v_and_b32_e32 v76, 0x7fffffff, v222
	v_and_b32_e32 v67, 0x7fffffff, v67
	v_and_b32_e32 v66, 0x7fffffff, v66
	v_and_b32_e32 v64, 0x7fffffff, v64
	v_and_b32_e32 v65, 0x7fffffff, v192
	v_pk_fma_f32 v[88:89], v[172:173], v[78:79], v[152:153]
	v_pk_fma_f32 v[78:79], v[172:173], v[66:67], v[152:153]
	v_pk_fma_f32 v[76:77], v[172:173], v[76:77], v[152:153]
	v_pk_fma_f32 v[74:75], v[172:173], v[74:75], v[152:153]
	v_pk_fma_f32 v[72:73], v[172:173], v[72:73], v[152:153]
	v_pk_fma_f32 v[70:71], v[172:173], v[70:71], v[152:153]
	v_pk_fma_f32 v[68:69], v[172:173], v[68:69], v[152:153]
	v_pk_fma_f32 v[66:67], v[172:173], v[224:225], v[152:153]
	v_pk_fma_f32 v[64:65], v[174:175], v[64:65], v[154:155]

; #define LAS __attribute__((address_space(3)))
; __device__ __forceinline__ void tile_body(bool DIAG, const LAS unsigned char* kb, const LAS unsigned char* vb, int krow, int jm, int hh, int rr, float d00, float m2, float sm2, float M0,
;                                           const bf16x8 (&qf)[4], f32x16 (&O)[4], float& ls) {
;     ...
;         for (int t4 = 0; t4 < 4; ++t4) { const int c = jm * 8 + 2 * t4 + hh, kr = 32 * sb + krow;
;             kf[sb][t4] = *(const LAS bf16x8*)(kb + kr * 256 + ((c ^ (kr & 15)) * 16)); }
;     f32x16 s0, s1;
;     if (!DIAG) { const float base0 = -M0 - sm2 * d00, base1 = base0 + sm2 * 32.0f;
; #pragma unroll
;         for (int r = 0; r < 16; ++r) { const float cr = (float)(16 * (r >> 3) + (r & 7)); s0[r] = fmaf(sm2, cr, base0); s1[r] = fmaf(sm2, cr, base1); }
;     } else {
; #pragma unroll
;         for (int r = 0; r < 16; ++r) { const float cr = (float)(16 * (r >> 3) + (r & 7)); s0[r] = fmaf(-m2, fabsf(d00 - cr), -M0); s1[r] = fmaf(-m2, fabsf(d00 - 32.0f - cr), -M0); }
;     }
; __device__ __forceinline__ void attn_phase(LAS unsigned char* lds, const bf16_t* Z, const bf16_t* VT, bf16_t* Y, const float* subln, float lam, float lam_init, float M0, unsigned* ctr, LAS int* s_unit, int wid_s_) {
;     ...
;             for (int half = 0; half < 2; ++half) { const int t = 2 * T + half;
;                 if (t >= wlo && t <= whi) {
;                     const LAS unsigned char* kb = lds + (2 * b + half) * BUF; const LAS unsigned char* vb = kb + KBYTES;
;                     const int k0 = t * 64;
;                     const float d00 = (float)(qw + rr - (k0 + 8 * hh));
;                     const bool left = (k0 + 63 <= qw), right = (k0 >= qw + 31);
;                     tile_body(!(left || right), kb, vb, krow, jm, hh, rr, d00, m2, right ? -m2 : m2, M0, qf, O, ls);
.Ldma_mid_skip:
	s_add_i32 s2, s26, 1
	s_cmp_lt_u32 s2, s51
	s_cbranch_scc1 .LBB0_1298
	s_cmp_ge_i32 s26, s84
	s_cbranch_scc1 .LBB0_1298
	ds_read_b128 v[114:117], v180 offset:32768
	ds_read_b128 v[130:133], v180 offset:40960
	ds_read_b128 v[118:121], v181 offset:32768
	ds_read_b128 v[134:137], v181 offset:40960
	ds_read_b128 v[122:125], v182 offset:32768
	ds_read_b128 v[138:141], v182 offset:40960
	ds_read_b128 v[126:129], v183 offset:32768
	ds_read_b128 v[142:145], v183 offset:40960
	s_add_i32 s16, s85, 64
	s_add_i32 s2, s85, 0x7f
	v_subrev_u32_e32 v64, 64, v193
	v_cvt_f32_i32_e32 v184, v64
	s_cmp_lt_i32 s16, s50
	s_cselect_b64 s[16:17], -1, 0
	s_cbranch_scc0 .Llin1
	s_cmp_gt_i32 s2, s40
	s_cbranch_scc1 .Ldiag1
.Llin1:
	v_cndmask_b32_e64 v78, -v171, v171, s[16:17]
	v_fma_f32 v94, -v78, v184, -v201
	v_fmamk_f32 v194, v78, 0x42000000, v94
	v_fma_f32 v80, 0, v78, v94
	v_fma_f32 v64, 0, v78, v194
	v_add_f32_e32 v81, v78, v94
	v_add_f32_e32 v65, v78, v194
	v_fma_f32 v82, v78, s80, v94
	v_fma_f32 v83, v78, s81, v94
	v_fma_f32 v66, v78, s80, v194
	v_fma_f32 v67, v78, s81, v194
	v_fma_f32 v84, v78, s66, v94
	v_fma_f32 v85, v78, s67, v94
	v_fma_f32 v68, v78, s66, v194
	v_fma_f32 v69, v78, s67, v194
	v_fma_f32 v86, v78, s74, v94
	v_fma_f32 v87, v78, s75, v94
	v_fma_f32 v70, v78, s74, v194
	v_fma_f32 v71, v78, s75, v194
	v_fma_f32 v88, v78, s34, v94
	v_fma_f32 v89, v78, s35, v94
	v_fma_f32 v72, v78, s34, v194
	v_fma_f32 v73, v78, s35, v194
	v_fma_f32 v90, v78, s96, v94
	v_fma_f32 v91, v78, s97, v94
	v_fma_f32 v74, v78, s96, v194
	v_fma_f32 v75, v78, s97, v194
	v_fma_f32 v92, v78, s52, v94
	v_fma_f32 v93, v78, s53, v94
	v_fma_f32 v76, v78, s52, v194
	v_fma_f32 v77, v78, s53, v194
	v_fma_f32 v95, v78, s55, v94
	v_fma_f32 v94, v78, s54, v94
	v_fma_f32 v79, v78, s55, v194
	v_fma_f32 v78, v78, s54, v194
	s_branch .LBB0_1297
.Ldiag1:
	v_pk_add_f32 v[66:67], v[184:185], s[56:57] op_sel_hi:[0,1]
	v_pk_add_f32 v[82:83], v[184:185], s[38:39] op_sel_hi:[0,1]
	v_add_f32_e32 v65, -1.0, v184
	v_add_f32_e32 v64, 0xc2000000, v184
	v_pk_add_f32 v[70:71], v[184:185], s[58:59] op_sel_hi:[0,1]
	v_pk_add_f32 v[74:75], v[184:185], s[60:61] op_sel_hi:[0,1]
	v_pk_add_f32 v[80:81], v[184:185], s[64:65] op_sel_hi:[0,1]
	v_pk_add_f32 v[84:85], v[184:185], s[30:31] op_sel_hi:[0,1]
	v_and_b32_e32 v67, 0x7fffffff, v67
	v_and_b32_e32 v66, 0x7fffffff, v66
	v_and_b32_e32 v83, 0x7fffffff, v83
	v_and_b32_e32 v82, 0x7fffffff, v82
	v_mov_b32_e32 v153, v152
	v_mov_b32_e32 v173, v172
	v_add_f32_e32 v189, -1.0, v64
	v_pk_add_f32 v[68:69], v[64:65], s[56:57] op_sel_hi:[0,1]
	v_pk_add_f32 v[72:73], v[64:65], s[58:59] op_sel_hi:[0,1]
	v_pk_add_f32 v[76:77], v[64:65], s[60:61] op_sel_hi:[0,1]
	v_pk_add_f32 v[78:79], v[184:185], s[62:63] op_sel_hi:[0,1]
	v_pk_add_f32 v[194:195], v[64:65], s[62:63] op_sel_hi:[0,1]
	v_pk_add_f32 v[218:219], v[64:65], s[64:65] op_sel_hi:[0,1]
	v_pk_add_f32 v[220:221], v[64:65], s[38:39] op_sel_hi:[0,1]
	v_and_b32_e32 v71, 0x7fffffff, v71
	v_and_b32_e32 v70, 0x7fffffff, v70
	v_and_b32_e32 v75, 0x7fffffff, v75
	v_and_b32_e32 v74, 0x7fffffff, v74
	v_and_b32_e32 v81, 0x7fffffff, v81
	v_and_b32_e32 v80, 0x7fffffff, v80
	v_and_b32_e32 v85, 0x7fffffff, v85
	v_and_b32_e32 v84, 0x7fffffff, v84
	v_and_b32_e32 v222, 0x7fffffff, v184
	v_and_b32_e32 v223, 0x7fffffff, v65
	v_pk_fma_f32 v[92:93], v[172:173], v[82:83], v[152:153]
	v_pk_fma_f32 v[82:83], v[172:173], v[66:67], v[152:153]
	v_pk_add_f32 v[66:67], v[64:65], s[30:31] op_sel_hi:[0,1]
	v_and_b32_e32 v79, 0x7fffffff, v79
	v_and_b32_e32 v78, 0x7fffffff, v78
	v_pk_fma_f32 v[94:95], v[172:173], v[84:85], v[152:153]
	v_pk_fma_f32 v[90:91], v[172:173], v[80:81], v[152:153]
	v_pk_fma_f32 v[86:87], v[172:173], v[74:75], v[152:153]
	v_pk_fma_f32 v[84:85], v[172:173], v[70:71], v[152:153]
	v_pk_fma_f32 v[80:81], v[174:175], v[222:223], v[154:155]
	v_and_b32_e32 v223, 0x7fffffff, v69
	v_and_b32_e32 v222, 0x7fffffff, v68
	v_and_b32_e32 v69, 0x7fffffff, v73
	v_and_b32_e32 v68, 0x7fffffff, v72
	v_and_b32_e32 v71, 0x7fffffff, v77
	v_and_b32_e32 v70, 0x7fffffff, v76
	v_and_b32_e32 v73, 0x7fffffff, v195
	v_and_b32_e32 v72, 0x7fffffff, v194
	v_and_b32_e32 v75, 0x7fffffff, v219
	v_and_b32_e32 v74, 0x7fffffff, v218
	v_and_b32_e32 v77, 0x7fffffff, v221
	v_and_b32_e32 v76, 0x7fffffff, v220
	v_and_b32_e32 v67, 0x7fffffff, v67
	v_and_b32_e32 v66, 0x7fffffff, v66
	v_and_b32_e32 v64, 0x7fffffff, v64
	v_and_b32_e32 v65, 0x7fffffff, v189
	v_pk_fma_f32 v[88:89], v[172:173], v[78:79], v[152:153]
	v_pk_fma_f32 v[78:79], v[172:173], v[66:67], v[152:153]
	v_pk_fma_f32 v[76:77], v[172:173], v[76:77], v[152:153]
	v_pk_fma_f32 v[74:75], v[172:173], v[74:75], v[152:153]
	v_pk_fma_f32 v[72:73], v[172:173], v[72:73], v[152:153]
	v_pk_fma_f32 v[70:71], v[172:173], v[70:71], v[152:153]
	v_pk_fma_f32 v[68:69], v[172:173], v[68:69], v[152:153]
	v_pk_fma_f32 v[66:67], v[172:173], v[222:223], v[152:153]
	v_pk_fma_f32 v[64:65], v[174:175], v[64:65], v[154:155]
	s_branch .LBB0_1297
